# non-temporal hint on the weight-conversion routine's bf16 tile stores (they are not re-read until a later phase)
# baseline (speedup 1.0000x reference)
; __device__ __forceinline__ unsigned pk2(float lo, float hi) { const hf32x2 v = {lo, hi}; return __builtin_bit_cast(unsigned, __builtin_convertvector(v, hbf16x2)); }
; __device__ __forceinline__ void tconv_tile_w(const float* src, int N, int kb, int nb, bf16_t* dst, int ldd, float* tile, const float* kscale = nullptr) {
;     ...
;     for (int p = 0; p < 8; ++p) { const int idx = tid + 512 * p, r = idx >> 6, c4 = idx & 63;
;         float* t = tile + r * 257 + c4 * 4; t[0] = v[p][0]; t[1] = v[p][1]; t[2] = v[p][2]; t[3] = v[p][3]; }
;     __syncthreads();
; #pragma unroll
;     for (int q = 0; q < 4; ++q) { const int id = tid + 512 * q, n = id >> 3, k8 = id & 7;
;         const float* s = tile + (k8 * 8) * 257 + n;
;         u32x4 o; o.x = pk2(s[0], s[257]); o.y = pk2(s[2 * 257], s[3 * 257]); o.z = pk2(s[4 * 257], s[5 * 257]); o.w = pk2(s[6 * 257], s[7 * 257]);
;         *(u32x4*)(dst + (size_t)(nb * 256 + n) * ldd + kb * 64 + k8 * 8) = o; }
.Ltc_pnosc_77:
	v_cvt_pk_bf16_f32 v64, v0, v4
	v_cvt_pk_bf16_f32 v65, v1, v5
	v_cvt_pk_bf16_f32 v66, v2, v6
	v_cvt_pk_bf16_f32 v67, v3, v7
	v_cvt_pk_bf16_f32 v68, v8, v12
	v_cvt_pk_bf16_f32 v69, v9, v13
	v_cvt_pk_bf16_f32 v70, v10, v14
	v_cvt_pk_bf16_f32 v71, v11, v15
	v_cvt_pk_bf16_f32 v72, v16, v20
	v_cvt_pk_bf16_f32 v73, v17, v21
	v_cvt_pk_bf16_f32 v74, v18, v22
	v_cvt_pk_bf16_f32 v75, v19, v23
	v_cvt_pk_bf16_f32 v76, v24, v28
	v_cvt_pk_bf16_f32 v77, v25, v29
	v_cvt_pk_bf16_f32 v78, v26, v30
	v_cvt_pk_bf16_f32 v79, v27, v31
	ds_write2_b32 v114, v64, v65 offset1:1
	ds_write2_b32 v114, v66, v67 offset0:2 offset1:3
	ds_write2_b32 v115, v68, v69 offset1:1
	ds_write2_b32 v115, v70, v71 offset0:2 offset1:3
	ds_write2_b32 v116, v72, v73 offset1:1
	ds_write2_b32 v116, v74, v75 offset0:2 offset1:3
	ds_write2_b32 v117, v76, v77 offset1:1
	ds_write2_b32 v117, v78, v79 offset0:2 offset1:3
	v_add_u32_e32 v113, 0, v108
	v_mad_u32_u24 v109, v113, s52, v107
	v_add_u32_e32 v113, 64, v108
	v_mad_u32_u24 v110, v113, s52, v107
	v_add_u32_e32 v113, 128, v108
	v_mad_u32_u24 v111, v113, s52, v107
	v_add_u32_e32 v113, 192, v108
	v_mad_u32_u24 v112, v113, s52, v107
	s_waitcnt lgkmcnt(0)
	s_barrier
	ds_read_b32 v80, v106 offset:0
	ds_read_b32 v81, v106 offset:1028
	ds_read_b32 v82, v106 offset:2056
	ds_read_b32 v83, v106 offset:3084
	ds_read_b32 v84, v106 offset:256
	ds_read_b32 v85, v106 offset:1284
	ds_read_b32 v86, v106 offset:2312
	ds_read_b32 v87, v106 offset:3340
	ds_read_b32 v88, v106 offset:512
	ds_read_b32 v89, v106 offset:1540
	ds_read_b32 v90, v106 offset:2568
	ds_read_b32 v91, v106 offset:3596
	ds_read_b32 v92, v106 offset:768
	ds_read_b32 v93, v106 offset:1796
	ds_read_b32 v94, v106 offset:2824
	ds_read_b32 v95, v106 offset:3852
	s_waitcnt lgkmcnt(12)
	global_store_dwordx4 v109, v[80:83], s[50:51] nt
	s_waitcnt lgkmcnt(8)
	global_store_dwordx4 v110, v[84:87], s[50:51] nt
	s_waitcnt lgkmcnt(4)
	global_store_dwordx4 v111, v[88:91], s[50:51] nt
	s_waitcnt lgkmcnt(0)
	global_store_dwordx4 v112, v[92:95], s[50:51] nt
	s_cmp_eq_u32 s43, 0
	s_cbranch_scc1 .Ltc_exit_1
	s_waitcnt lgkmcnt(0)
	s_mov_b64 s[50:51], s[46:47]
	s_mov_b32 s52, s48
	s_mov_b32 s59, s61
	s_mov_b64 s[68:69], s[76:77]
	s_mov_b64 s[70:71], s[78:79]
	s_mov_b64 s[72:73], s[80:81]
	s_mov_b64 s[74:75], s[82:83]
	s_add_u32 s29, s29, s63
	s_mov_b32 s62, 0

; __device__ __forceinline__ unsigned pk2(float lo, float hi) { const hf32x2 v = {lo, hi}; return __builtin_bit_cast(unsigned, __builtin_convertvector(v, hbf16x2)); }
; __device__ __forceinline__ void tconv_tile_w(const float* src, int N, int kb, int nb, bf16_t* dst, int ldd, float* tile, const float* kscale = nullptr) {
;     ...
;     for (int p = 0; p < 8; ++p) { const int idx = tid + 512 * p, r = idx >> 6, c4 = idx & 63;
;         float* t = tile + r * 257 + c4 * 4; t[0] = v[p][0]; t[1] = v[p][1]; t[2] = v[p][2]; t[3] = v[p][3]; }
;     __syncthreads();
; #pragma unroll
;     for (int q = 0; q < 4; ++q) { const int id = tid + 512 * q, n = id >> 3, k8 = id & 7;
;         const float* s = tile + (k8 * 8) * 257 + n;
;         u32x4 o; o.x = pk2(s[0], s[257]); o.y = pk2(s[2 * 257], s[3 * 257]); o.z = pk2(s[4 * 257], s[5 * 257]); o.w = pk2(s[6 * 257], s[7 * 257]);
;         *(u32x4*)(dst + (size_t)(nb * 256 + n) * ldd + kb * 64 + k8 * 8) = o; }
.Ltc_pnosc_117:
	v_cvt_pk_bf16_f32 v64, v32, v36
	v_cvt_pk_bf16_f32 v65, v33, v37
	v_cvt_pk_bf16_f32 v66, v34, v38
	v_cvt_pk_bf16_f32 v67, v35, v39
	v_cvt_pk_bf16_f32 v68, v40, v44
	v_cvt_pk_bf16_f32 v69, v41, v45
	v_cvt_pk_bf16_f32 v70, v42, v46
	v_cvt_pk_bf16_f32 v71, v43, v47
	v_cvt_pk_bf16_f32 v72, v48, v52
	v_cvt_pk_bf16_f32 v73, v49, v53
	v_cvt_pk_bf16_f32 v74, v50, v54
	v_cvt_pk_bf16_f32 v75, v51, v55
	v_cvt_pk_bf16_f32 v76, v56, v60
	v_cvt_pk_bf16_f32 v77, v57, v61
	v_cvt_pk_bf16_f32 v78, v58, v62
	v_cvt_pk_bf16_f32 v79, v59, v63
	ds_write2_b32 v118, v64, v65 offset1:1
	ds_write2_b32 v118, v66, v67 offset0:2 offset1:3
	ds_write2_b32 v119, v68, v69 offset1:1
	ds_write2_b32 v119, v70, v71 offset0:2 offset1:3
	ds_write2_b32 v120, v72, v73 offset1:1
	ds_write2_b32 v120, v74, v75 offset0:2 offset1:3
	ds_write2_b32 v121, v76, v77 offset1:1
	ds_write2_b32 v121, v78, v79 offset0:2 offset1:3
	v_add_u32_e32 v113, 0, v108
	v_mad_u32_u24 v109, v113, s52, v107
	v_add_u32_e32 v113, 64, v108
	v_mad_u32_u24 v110, v113, s52, v107
	v_add_u32_e32 v113, 128, v108
	v_mad_u32_u24 v111, v113, s52, v107
	v_add_u32_e32 v113, 192, v108
	v_mad_u32_u24 v112, v113, s52, v107
	s_waitcnt lgkmcnt(0)
	s_barrier
	ds_read_b32 v80, v106 offset:33024
	ds_read_b32 v81, v106 offset:34052
	ds_read_b32 v82, v106 offset:35080
	ds_read_b32 v83, v106 offset:36108
	ds_read_b32 v84, v106 offset:33280
	ds_read_b32 v85, v106 offset:34308
	ds_read_b32 v86, v106 offset:35336
	ds_read_b32 v87, v106 offset:36364
	ds_read_b32 v88, v106 offset:33536
	ds_read_b32 v89, v106 offset:34564
	ds_read_b32 v90, v106 offset:35592
	ds_read_b32 v91, v106 offset:36620
	ds_read_b32 v92, v106 offset:33792
	ds_read_b32 v93, v106 offset:34820
	ds_read_b32 v94, v106 offset:35848
	ds_read_b32 v95, v106 offset:36876
	s_waitcnt lgkmcnt(12)
	global_store_dwordx4 v109, v[80:83], s[50:51] nt
	s_waitcnt lgkmcnt(8)
	global_store_dwordx4 v110, v[84:87], s[50:51] nt
	s_waitcnt lgkmcnt(4)
	global_store_dwordx4 v111, v[88:91], s[50:51] nt
	s_waitcnt lgkmcnt(0)
	global_store_dwordx4 v112, v[92:95], s[50:51] nt
	s_cmp_eq_u32 s43, 0
	s_cbranch_scc1 .Ltc_exit_1
	s_waitcnt lgkmcnt(0)
	s_mov_b64 s[50:51], s[46:47]
	s_mov_b32 s52, s48
	s_mov_b32 s59, s61
	s_mov_b64 s[68:69], s[76:77]
	s_mov_b64 s[70:71], s[78:79]
	s_mov_b64 s[72:73], s[80:81]
	s_mov_b64 s[74:75], s[82:83]
	s_branch .Ltc_loop_37
